# phase-13 q/k epilogue: one 16-byte store per lane per rotary group (dims permuted identically for q and k) instead of two 8-byte stores; no head-slot swizzle
# speedup vs baseline: 1.0022x; 1.0022x over previous
; __device__ __forceinline__ unsigned cvt_pk_bf16(float lo, float hi) { unsigned r; asm volatile("v_cvt_pk_bf16_f32 %0, %1, %2" : "=v"(r) : "v"(lo), "v"(hi)); return r; }
;     __device__ __forceinline__ void operator()(const f32x4 (&acc)[2][2][4][2], const Unit& u, int wr, int wc, int fr, int fq) const {
;         const int row0 = u.pm * 256 + wr * 64 + fr;
;         if (u.pn < 16) {
;             const float qs = u.pn < 8 ? (0.125f * 1.44269504089f) : 1.0f;
;             const int j0 = 16 * (wc & 1) + 4 * fq;
; #pragma unroll
;             for (int ai = 0; ai < 2; ++ai)
; #pragma unroll
;                 for (int m = 0; m < 4; ++m) { const int row = row0 + ai * 128 + m * 16, t = row & 4095;
;                     const f32x4 c4 = *(const f32x4*)(cs + t * 32 + j0), s4 = *(const f32x4*)(sn + t * 32 + j0);
; #pragma unroll
;                     for (int bj = 0; bj < 2; ++bj) { const int hh = 2 * bj + (wc >> 1);
;                         const f32x4 x1 = acc[ai][bj][m][0], x2 = acc[ai][bj][m][1]; float o1[4], o2[4];
; #pragma unroll
;                         for (int i = 0; i < 4; ++i) { o1[i] = (x1[i] * c4[i] - x2[i] * s4[i]) * qs; o2[i] = (x2[i] * c4[i] + x1[i] * s4[i]) * qs; }
;                         u16* dst = QK + (size_t)row * 4096 + u.pn * 256 + 64 * hh + j0;
;                         u32x2 a, b; a[0] = cvt_pk_bf16(o1[0], o1[1]); a[1] = cvt_pk_bf16(o1[2], o1[3]); b[0] = cvt_pk_bf16(o2[0], o2[1]); b[1] = cvt_pk_bf16(o2[2], o2[3]);
;                         *(u32x2*)dst = a; *(u32x2*)(dst + 32) = b; } }
.LBB0_1960:
	s_andn2_b64 vcc, exec, s[30:31]
	s_cbranch_vccnz .LBB0_1953
	v_lshlrev_b32_e32 v230, 1, v146
	v_mov_b32_e32 v231, 0
	v_lshlrev_b32_e32 v132, 7, v148
	v_and_b32_e32 v132, 0x7e780, v132
	v_lshl_add_u64 v[160:161], v[134:135], 0, v[132:133]
	v_lshl_add_u64 v[166:167], v[136:137], 0, v[132:133]
	global_load_dwordx4 v[162:165], v[160:161], off
	s_nop 0
	global_load_dwordx4 v[166:169], v[166:167], off
	s_cmp_lt_i32 s60, 8
	v_ashrrev_i32_e32 v149, 31, v148
	s_cselect_b64 vcc, -1, 0
	s_lshl_b32 s30, s60, 8
	v_lshlrev_b64 v[186:187], 13, v[148:149]
	s_ashr_i32 s31, s30, 31
	v_mov_b32_e32 v172, v124
	v_mov_b32_e32 v173, v120
	v_mov_b32_e32 v174, v120
	v_mov_b32_e32 v175, v124
	v_mov_b32_e32 v120, v125
	v_mov_b32_e32 v124, v121
	v_mov_b32_e32 v176, v126
	v_mov_b32_e32 v177, v122
	v_mov_b32_e32 v178, v122
	v_mov_b32_e32 v122, v127
	v_mov_b32_e32 v180, v116
	v_mov_b32_e32 v181, v112
	v_mov_b32_e32 v182, v112
	v_mov_b32_e32 v183, v116
	v_mov_b32_e32 v112, v117
	v_mov_b32_e32 v116, v113
	v_lshl_add_u64 v[186:187], s[96:97], 0, v[186:187]
	s_lshl_b64 s[30:31], s[30:31], 1
	v_mov_b32_e32 v179, v126
	v_mov_b32_e32 v126, v123
	v_lshl_add_u64 v[186:187], v[186:187], 0, s[30:31]
	v_mov_b32_e32 v147, v133
	v_cndmask_b32_e32 v160, 1.0, v159, vcc
	v_lshl_add_u64 v[186:187], v[186:187], 0, s[6:7]
	v_lshl_add_u64 v[186:187], v[186:187], 0, v[230:231]
	v_mov_b32_e32 v185, v114
	v_mov_b32_e32 v184, v118
	s_waitcnt vmcnt(0)
	v_mov_b32_e32 v188, v162
	v_mov_b32_e32 v189, v166
	v_mov_b32_e32 v166, v163
	v_mov_b32_e32 v162, v164
	v_mov_b32_e32 v163, v168
	v_mov_b32_e32 v168, v165
	v_pk_mul_f32 v[164:165], v[172:173], v[188:189]
	v_pk_mul_f32 v[172:173], v[174:175], v[188:189]
	v_pk_mul_f32 v[120:121], v[120:121], v[166:167]
	v_pk_mul_f32 v[124:125], v[124:125], v[166:167]
	v_pk_mul_f32 v[174:175], v[176:177], v[162:163]
	v_pk_mul_f32 v[122:123], v[122:123], v[168:169]
	v_pk_mul_f32 v[112:113], v[112:113], v[166:167]
	v_pk_mul_f32 v[116:117], v[116:117], v[166:167]
	v_pk_mul_f32 v[176:177], v[178:179], v[162:163]
	v_pk_mul_f32 v[126:127], v[126:127], v[168:169]
	v_sub_f32_e32 v132, v164, v165
	v_add_f32_e32 v149, v172, v173
	v_sub_f32_e32 v120, v120, v121
	v_add_f32_e32 v121, v124, v125
	v_sub_f32_e32 v124, v174, v175
	v_sub_f32_e32 v122, v122, v123
	v_sub_f32_e32 v112, v112, v113
	v_add_f32_e32 v113, v116, v117
	v_add_f32_e32 v125, v176, v177
	v_add_f32_e32 v123, v126, v127
	v_mul_f32_e32 v116, v160, v132
	v_mul_f32_e32 v117, v160, v149
	v_mul_f32_e32 v120, v160, v120
	v_mul_f32_e32 v124, v160, v124
	v_mul_f32_e32 v122, v160, v122
	v_mul_f32_e32 v132, v160, v112
	v_mul_f32_e32 v149, v160, v113
	v_cvt_pk_bf16_f32 v112, v116, v120
	v_cvt_pk_bf16_f32 v113, v124, v122
	v_mul_f32_e32 v121, v160, v121
	v_mul_f32_e32 v125, v160, v125
	v_mul_f32_e32 v123, v160, v123
	v_cvt_pk_bf16_f32 v116, v117, v121
	v_cvt_pk_bf16_f32 v117, v125, v123
	v_mov_b32_e32 v232, v112
	v_mov_b32_e32 v233, v113
	v_mov_b32_e32 v234, v116
	v_mov_b32_e32 v235, v117
	global_store_dwordx4 v[186:187], v[232:235], off
	v_mov_b32_e32 v112, v114
	v_mov_b32_e32 v113, v118
	v_pk_mul_f32 v[112:113], v[112:113], v[162:163]
	v_mov_b32_e32 v114, v119
	v_add_f32_e32 v112, v112, v113
	v_mul_f32_e32 v117, v160, v112
	v_pk_mul_f32 v[112:113], v[114:115], v[168:169]
	v_mov_b32_e32 v118, v115
	v_sub_f32_e32 v112, v112, v113
	v_pk_mul_f32 v[178:179], v[180:181], v[188:189]
	v_pk_mul_f32 v[166:167], v[184:185], v[162:163]
	v_mul_f32_e32 v114, v160, v112
	v_pk_mul_f32 v[112:113], v[118:119], v[168:169]
	v_pk_mul_f32 v[180:181], v[182:183], v[188:189]
	v_sub_f32_e32 v126, v178, v179
	v_sub_f32_e32 v151, v166, v167
	v_add_f32_e32 v112, v112, v113
	v_add_f32_e32 v127, v180, v181
	v_mul_f32_e32 v126, v160, v126
	v_mul_f32_e32 v116, v160, v151
	v_mul_f32_e32 v115, v160, v112
	v_cvt_pk_bf16_f32 v112, v126, v132
	v_cvt_pk_bf16_f32 v113, v116, v114
	v_or_b32_e32 v120, 16, v148
	v_mul_f32_e32 v127, v160, v127
	v_cvt_pk_bf16_f32 v114, v127, v149
	v_cvt_pk_bf16_f32 v115, v117, v115
	v_mov_b32_e32 v232, v112
	v_mov_b32_e32 v233, v113
	v_mov_b32_e32 v234, v114
	v_mov_b32_e32 v235, v115
	global_store_dwordx4 v[186:187], v[232:235], off offset:256
	v_lshlrev_b32_e32 v112, 7, v120
	v_and_b32_e32 v132, 0x7ef80, v112
	v_lshl_add_u64 v[112:113], v[134:135], 0, v[132:133]
	v_lshl_add_u64 v[116:117], v[136:137], 0, v[132:133]
	global_load_dwordx4 v[112:115], v[112:113], off
	s_nop 0
	global_load_dwordx4 v[116:119], v[116:117], off
	v_ashrrev_i32_e32 v121, 31, v120
	v_mov_b32_e32 v122, v108
	v_mov_b32_e32 v123, v104
	v_mov_b32_e32 v124, v104
	v_mov_b32_e32 v125, v108
	v_mov_b32_e32 v104, v109
	v_mov_b32_e32 v108, v105
	v_mov_b32_e32 v126, v110
	v_mov_b32_e32 v127, v106
	v_lshlrev_b64 v[120:121], 13, v[120:121]
	v_mov_b32_e32 v162, v106
	v_mov_b32_e32 v163, v110
	v_mov_b32_e32 v106, v111
	v_mov_b32_e32 v110, v107
	v_lshl_add_u64 v[120:121], s[96:97], 0, v[120:121]
	v_mov_b32_e32 v165, v96
	v_mov_b32_e32 v166, v96
	v_lshl_add_u64 v[120:121], v[120:121], 0, s[30:31]
	v_lshl_add_u64 v[120:121], v[120:121], 0, s[6:7]
	v_lshl_add_u64 v[120:121], v[120:121], 0, v[230:231]
	v_mov_b32_e32 v167, v100
	v_mov_b32_e32 v164, v100
	v_mov_b32_e32 v100, v97
	v_ashrrev_i32_e32 v151, 31, v150
	s_waitcnt vmcnt(0)
; __device__ __forceinline__ unsigned cvt_pk_bf16(float lo, float hi) { unsigned r; asm volatile("v_cvt_pk_bf16_f32 %0, %1, %2" : "=v"(r) : "v"(lo), "v"(hi)); return r; }
;     __device__ __forceinline__ void operator()(const f32x4 (&acc)[2][2][4][2], const Unit& u, int wr, int wc, int fr, int fq) const {
;         const int row0 = u.pm * 256 + wr * 64 + fr;
;         if (u.pn < 16) {
;             const float qs = u.pn < 8 ? (0.125f * 1.44269504089f) : 1.0f;
;             const int j0 = 16 * (wc & 1) + 4 * fq;
; #pragma unroll
;             for (int ai = 0; ai < 2; ++ai)
; #pragma unroll
;                 for (int m = 0; m < 4; ++m) { const int row = row0 + ai * 128 + m * 16, t = row & 4095;
;                     const f32x4 c4 = *(const f32x4*)(cs + t * 32 + j0), s4 = *(const f32x4*)(sn + t * 32 + j0);
; #pragma unroll
;                     for (int bj = 0; bj < 2; ++bj) { const int hh = 2 * bj + (wc >> 1);
;                         const f32x4 x1 = acc[ai][bj][m][0], x2 = acc[ai][bj][m][1]; float o1[4], o2[4];
; #pragma unroll
;                         for (int i = 0; i < 4; ++i) { o1[i] = (x1[i] * c4[i] - x2[i] * s4[i]) * qs; o2[i] = (x2[i] * c4[i] + x1[i] * s4[i]) * qs; }
;                         u16* dst = QK + (size_t)row * 4096 + u.pn * 256 + 64 * hh + j0;
;                         u32x2 a, b; a[0] = cvt_pk_bf16(o1[0], o1[1]); a[1] = cvt_pk_bf16(o1[2], o1[3]); b[0] = cvt_pk_bf16(o2[0], o2[1]); b[1] = cvt_pk_bf16(o2[2], o2[3]);
;                         *(u32x2*)dst = a; *(u32x2*)(dst + 32) = b; } }
	v_mov_b32_e32 v168, v112
	v_mov_b32_e32 v169, v116
	v_mov_b32_e32 v116, v113
	v_mov_b32_e32 v112, v114
	v_mov_b32_e32 v113, v118
	v_mov_b32_e32 v118, v115
	v_pk_mul_f32 v[114:115], v[122:123], v[168:169]
	v_pk_mul_f32 v[122:123], v[124:125], v[168:169]
	v_pk_mul_f32 v[104:105], v[104:105], v[116:117]
	v_pk_mul_f32 v[108:109], v[108:109], v[116:117]
	v_pk_mul_f32 v[124:125], v[126:127], v[112:113]
	v_pk_mul_f32 v[106:107], v[106:107], v[118:119]
	v_pk_mul_f32 v[110:111], v[110:111], v[118:119]
	v_sub_f32_e32 v96, v114, v115
	v_add_f32_e32 v114, v122, v123
	v_sub_f32_e32 v104, v104, v105
	v_add_f32_e32 v105, v108, v109
	v_sub_f32_e32 v108, v124, v125
	v_pk_mul_f32 v[126:127], v[162:163], v[112:113]
	v_sub_f32_e32 v106, v106, v107
	v_add_f32_e32 v107, v110, v111
	v_mul_f32_e32 v111, v160, v114
	v_mul_f32_e32 v104, v160, v104
	v_mul_f32_e32 v114, v160, v105
	v_mul_f32_e32 v105, v160, v108
	v_add_f32_e32 v109, v126, v127
	v_mul_f32_e32 v96, v160, v96
	v_mul_f32_e32 v106, v160, v106
	v_mul_f32_e32 v107, v160, v107
	v_cvt_pk_bf16_f32 v104, v96, v104
	v_cvt_pk_bf16_f32 v105, v105, v106
	v_mul_f32_e32 v108, v160, v109
	v_cvt_pk_bf16_f32 v106, v111, v114
	v_cvt_pk_bf16_f32 v107, v108, v107
	v_mov_b32_e32 v232, v104
	v_mov_b32_e32 v233, v105
	v_mov_b32_e32 v234, v106
	v_mov_b32_e32 v235, v107
	global_store_dwordx4 v[120:121], v[232:235], off
	v_pk_mul_f32 v[104:105], v[166:167], v[168:169]
	v_pk_mul_f32 v[162:163], v[164:165], v[168:169]
	v_add_f32_e32 v96, v104, v105
	v_mul_f32_e32 v106, v160, v96
	v_mov_b32_e32 v96, v101
	v_pk_mul_f32 v[104:105], v[96:97], v[116:117]
	v_sub_f32_e32 v110, v162, v163
	v_sub_f32_e32 v96, v104, v105
	v_mul_f32_e32 v104, v160, v96
	v_pk_mul_f32 v[96:97], v[100:101], v[116:117]
	v_mul_f32_e32 v109, v160, v110
	v_add_f32_e32 v96, v96, v97
	v_mul_f32_e32 v100, v160, v96
	v_mov_b32_e32 v96, v102
	v_mov_b32_e32 v97, v98
	v_pk_mul_f32 v[96:97], v[96:97], v[112:113]
	v_mov_b32_e32 v107, v88
	v_sub_f32_e32 v96, v96, v97
	v_mul_f32_e32 v101, v160, v96
	v_mov_b32_e32 v96, v98
	v_mov_b32_e32 v97, v102
	v_pk_mul_f32 v[96:97], v[96:97], v[112:113]
	v_mov_b32_e32 v98, v103
	v_add_f32_e32 v96, v96, v97
	v_mul_f32_e32 v105, v160, v96
	v_pk_mul_f32 v[96:97], v[98:99], v[118:119]
	v_mov_b32_e32 v102, v99
	v_sub_f32_e32 v96, v96, v97
	v_mul_f32_e32 v98, v160, v96
	v_pk_mul_f32 v[96:97], v[102:103], v[118:119]
	v_mov_b32_e32 v108, v88
	v_add_f32_e32 v96, v96, v97
	v_mul_f32_e32 v99, v160, v96
	v_cvt_pk_bf16_f32 v96, v109, v104
	v_cvt_pk_bf16_f32 v97, v101, v98
	v_or_b32_e32 v104, 32, v148
	v_cvt_pk_bf16_f32 v98, v106, v100
	v_cvt_pk_bf16_f32 v99, v105, v99
	v_mov_b32_e32 v232, v96
	v_mov_b32_e32 v233, v97
	v_mov_b32_e32 v234, v98
	v_mov_b32_e32 v235, v99
	global_store_dwordx4 v[120:121], v[232:235], off offset:256
	v_lshlrev_b32_e32 v96, 7, v104
	v_and_b32_e32 v132, 0x7f780, v96
	v_lshl_add_u64 v[96:97], v[134:135], 0, v[132:133]
	v_lshl_add_u64 v[100:101], v[136:137], 0, v[132:133]
	global_load_dwordx4 v[96:99], v[96:97], off
	s_nop 0
	global_load_dwordx4 v[100:103], v[100:101], off
	v_mov_b32_e32 v106, v92
	v_mov_b32_e32 v109, v92
	v_mov_b32_e32 v88, v93
	v_mov_b32_e32 v92, v89
	v_mov_b32_e32 v110, v94
	v_mov_b32_e32 v111, v90
	v_mov_b32_e32 v112, v90
	v_mov_b32_e32 v113, v94
	v_mov_b32_e32 v90, v95
	v_mov_b32_e32 v94, v91
	v_ashrrev_i32_e32 v105, 31, v104
	v_lshlrev_b64 v[104:105], 13, v[104:105]
	s_waitcnt vmcnt(0)
	v_mov_b32_e32 v114, v96
	v_mov_b32_e32 v115, v100
	v_mov_b32_e32 v100, v97
	v_mov_b32_e32 v96, v98
	v_mov_b32_e32 v97, v102
	v_mov_b32_e32 v102, v99
	v_pk_mul_f32 v[98:99], v[106:107], v[114:115]
	v_pk_mul_f32 v[106:107], v[108:109], v[114:115]
	v_pk_mul_f32 v[88:89], v[88:89], v[100:101]
	v_pk_mul_f32 v[92:93], v[92:93], v[100:101]
	v_pk_mul_f32 v[90:91], v[90:91], v[102:103]
	v_pk_mul_f32 v[94:95], v[94:95], v[102:103]
	v_sub_f32_e32 v98, v98, v99
	v_add_f32_e32 v99, v106, v107
	v_sub_f32_e32 v88, v88, v89
	v_add_f32_e32 v89, v92, v93
	v_sub_f32_e32 v90, v90, v91
	v_mul_f32_e32 v91, v160, v98
	v_mul_f32_e32 v98, v160, v99
	v_mul_f32_e32 v99, v160, v88
	v_add_f32_e32 v88, v94, v95
	v_mul_f32_e32 v106, v160, v89
	v_mul_f32_e32 v94, v160, v88
	v_lshl_add_u64 v[88:89], s[96:97], 0, v[104:105]
	v_pk_mul_f32 v[108:109], v[110:111], v[96:97]
	v_pk_mul_f32 v[110:111], v[112:113], v[96:97]
	v_lshl_add_u64 v[88:89], v[88:89], 0, s[30:31]
	v_sub_f32_e32 v92, v108, v109
	v_add_f32_e32 v93, v110, v111
	v_lshl_add_u64 v[88:89], v[88:89], 0, s[6:7]
	v_mul_f32_e32 v92, v160, v92
	v_mul_f32_e32 v93, v160, v93
	v_mul_f32_e32 v107, v160, v90
	v_lshl_add_u64 v[88:89], v[88:89], 0, v[230:231]
	v_cvt_pk_bf16_f32 v90, v91, v99
	v_cvt_pk_bf16_f32 v91, v92, v107
	v_cvt_pk_bf16_f32 v92, v98, v106
	v_cvt_pk_bf16_f32 v93, v93, v94
	v_mov_b32_e32 v232, v90
	v_mov_b32_e32 v233, v91
	v_mov_b32_e32 v234, v92
	v_mov_b32_e32 v235, v93
	global_store_dwordx4 v[88:89], v[232:235], off
	v_mov_b32_e32 v90, v84
	v_mov_b32_e32 v91, v80
	v_pk_mul_f32 v[90:91], v[90:91], v[114:115]
	v_mov_b32_e32 v94, v78
	v_sub_f32_e32 v90, v90, v91
	v_mul_f32_e32 v92, v160, v90
	v_mov_b32_e32 v90, v80
	v_mov_b32_e32 v91, v84
	v_pk_mul_f32 v[90:91], v[90:91], v[114:115]
	v_mov_b32_e32 v84, v81
	v_add_f32_e32 v80, v90, v91
	v_mul_f32_e32 v93, v160, v80
	v_mov_b32_e32 v80, v85
	v_pk_mul_f32 v[90:91], v[80:81], v[100:101]
	v_mov_b32_e32 v95, v74
	v_sub_f32_e32 v80, v90, v91
	v_mul_f32_e32 v90, v160, v80
	v_pk_mul_f32 v[80:81], v[84:85], v[100:101]
	s_nop 0
	v_add_f32_e32 v80, v80, v81
	v_mul_f32_e32 v84, v160, v80
	v_mov_b32_e32 v80, v86
	v_mov_b32_e32 v81, v82
	v_pk_mul_f32 v[80:81], v[80:81], v[96:97]
	s_nop 0
	v_sub_f32_e32 v80, v80, v81
	v_mul_f32_e32 v85, v160, v80
	v_mov_b32_e32 v80, v82
	v_mov_b32_e32 v81, v86
	v_pk_mul_f32 v[80:81], v[80:81], v[96:97]
	v_mov_b32_e32 v82, v87
	v_add_f32_e32 v80, v80, v81
	v_mul_f32_e32 v91, v160, v80
	v_pk_mul_f32 v[80:81], v[82:83], v[102:103]
	v_mov_b32_e32 v86, v83
	v_sub_f32_e32 v80, v80, v81
	v_mul_f32_e32 v82, v160, v80
	v_pk_mul_f32 v[80:81], v[86:87], v[102:103]
	s_nop 0
	v_add_f32_e32 v80, v80, v81
	v_mul_f32_e32 v83, v160, v80
	v_cvt_pk_bf16_f32 v80, v92, v90
	v_cvt_pk_bf16_f32 v81, v85, v82
	v_cvt_pk_bf16_f32 v82, v93, v84
	v_cvt_pk_bf16_f32 v83, v91, v83
	v_mov_b32_e32 v232, v80
	v_mov_b32_e32 v233, v81
	v_mov_b32_e32 v234, v82
	v_mov_b32_e32 v235, v83
	global_store_dwordx4 v[88:89], v[232:235], off offset:256
	v_or_b32_e32 v88, 48, v148
	v_lshlrev_b32_e32 v80, 7, v88
	v_and_b32_e32 v132, 0x7ff80, v80
	v_lshl_add_u64 v[80:81], v[134:135], 0, v[132:133]
	v_lshl_add_u64 v[84:85], v[136:137], 0, v[132:133]
	global_load_dwordx4 v[80:83], v[80:81], off
	s_nop 0
	global_load_dwordx4 v[84:87], v[84:85], off
	v_mov_b32_e32 v90, v76
	v_mov_b32_e32 v91, v72
	v_mov_b32_e32 v92, v72
	v_mov_b32_e32 v93, v76
	v_mov_b32_e32 v72, v77
	v_mov_b32_e32 v76, v73
	v_ashrrev_i32_e32 v89, 31, v88
	v_lshlrev_b64 v[88:89], 13, v[88:89]
	s_waitcnt vmcnt(0)
; __device__ __forceinline__ unsigned cvt_pk_bf16(float lo, float hi) { unsigned r; asm volatile("v_cvt_pk_bf16_f32 %0, %1, %2" : "=v"(r) : "v"(lo), "v"(hi)); return r; }
;     __device__ __forceinline__ void operator()(const f32x4 (&acc)[2][2][4][2], const Unit& u, int wr, int wc, int fr, int fq) const {
;     ...
;                 for (int m = 0; m < 4; ++m) { const int row = row0 + ai * 128 + m * 16, t = row & 4095;
;                     const f32x4 c4 = *(const f32x4*)(cs + t * 32 + j0), s4 = *(const f32x4*)(sn + t * 32 + j0);
; #pragma unroll
;                     for (int bj = 0; bj < 2; ++bj) { const int hh = 2 * bj + (wc >> 1);
;                         const f32x4 x1 = acc[ai][bj][m][0], x2 = acc[ai][bj][m][1]; float o1[4], o2[4];
; #pragma unroll
;                         for (int i = 0; i < 4; ++i) { o1[i] = (x1[i] * c4[i] - x2[i] * s4[i]) * qs; o2[i] = (x2[i] * c4[i] + x1[i] * s4[i]) * qs; }
;                         u16* dst = QK + (size_t)row * 4096 + u.pn * 256 + 64 * hh + j0;
;                         u32x2 a, b; a[0] = cvt_pk_bf16(o1[0], o1[1]); a[1] = cvt_pk_bf16(o1[2], o1[3]); b[0] = cvt_pk_bf16(o2[0], o2[1]); b[1] = cvt_pk_bf16(o2[2], o2[3]);
;                         *(u32x2*)dst = a; *(u32x2*)(dst + 32) = b; } }
	v_mov_b32_e32 v96, v80
	v_mov_b32_e32 v97, v84
	v_mov_b32_e32 v84, v81
	v_pk_mul_f32 v[90:91], v[90:91], v[96:97]
	v_pk_mul_f32 v[92:93], v[92:93], v[96:97]
	v_pk_mul_f32 v[72:73], v[72:73], v[84:85]
	v_pk_mul_f32 v[76:77], v[76:77], v[84:85]
	v_sub_f32_e32 v81, v90, v91
	v_mov_b32_e32 v80, v82
	v_add_f32_e32 v82, v92, v93
	v_sub_f32_e32 v72, v72, v73
	v_add_f32_e32 v73, v76, v77
	v_mul_f32_e32 v76, v160, v81
	v_mov_b32_e32 v81, v86
	v_mul_f32_e32 v77, v160, v82
	v_mul_f32_e32 v82, v160, v72
	v_mul_f32_e32 v90, v160, v73
	v_pk_mul_f32 v[72:73], v[94:95], v[80:81]
	v_mov_b32_e32 v86, v83
	v_sub_f32_e32 v72, v72, v73
	v_mul_f32_e32 v91, v160, v72
	v_mov_b32_e32 v72, v74
	v_mov_b32_e32 v73, v78
	v_pk_mul_f32 v[72:73], v[72:73], v[80:81]
	v_mov_b32_e32 v74, v79
	v_add_f32_e32 v72, v72, v73
	v_mul_f32_e32 v92, v160, v72
	v_pk_mul_f32 v[72:73], v[74:75], v[86:87]
	v_mov_b32_e32 v78, v75
	v_sub_f32_e32 v72, v72, v73
	v_mul_f32_e32 v83, v160, v72
	v_pk_mul_f32 v[72:73], v[78:79], v[86:87]
	v_cvt_pk_bf16_f32 v74, v76, v82
	v_cvt_pk_bf16_f32 v75, v91, v83
	v_cvt_pk_bf16_f32 v76, v77, v90
	s_nop 0
	v_add_f32_e32 v72, v72, v73
	v_mul_f32_e32 v78, v160, v72
	v_lshl_add_u64 v[72:73], s[96:97], 0, v[88:89]
	v_lshl_add_u64 v[72:73], v[72:73], 0, s[30:31]
	v_lshl_add_u64 v[72:73], v[72:73], 0, s[6:7]
	v_lshl_add_u64 v[72:73], v[72:73], 0, v[230:231]
	v_cvt_pk_bf16_f32 v77, v92, v78
	v_mov_b32_e32 v232, v74
	v_mov_b32_e32 v233, v75
	v_mov_b32_e32 v234, v76
	v_mov_b32_e32 v235, v77
	global_store_dwordx4 v[72:73], v[232:235], off
	v_mov_b32_e32 v74, v68
	v_mov_b32_e32 v75, v64
	v_pk_mul_f32 v[74:75], v[74:75], v[96:97]
	s_nop 0
	v_sub_f32_e32 v74, v74, v75
	v_mul_f32_e32 v76, v160, v74
	v_mov_b32_e32 v74, v64
	v_mov_b32_e32 v75, v68
	v_pk_mul_f32 v[74:75], v[74:75], v[96:97]
	v_mov_b32_e32 v68, v65
	v_add_f32_e32 v64, v74, v75
	v_mul_f32_e32 v77, v160, v64
	v_mov_b32_e32 v64, v69
	v_pk_mul_f32 v[74:75], v[64:65], v[84:85]
	s_nop 0
	v_sub_f32_e32 v64, v74, v75
	v_mul_f32_e32 v74, v160, v64
	v_pk_mul_f32 v[64:65], v[68:69], v[84:85]
	s_nop 0
	v_add_f32_e32 v64, v64, v65
	v_mul_f32_e32 v68, v160, v64
	v_mov_b32_e32 v64, v70
	v_mov_b32_e32 v65, v66
	v_pk_mul_f32 v[64:65], v[64:65], v[80:81]
	s_nop 0
	v_sub_f32_e32 v64, v64, v65
	v_mul_f32_e32 v69, v160, v64
	v_mov_b32_e32 v64, v66
	v_mov_b32_e32 v65, v70
	v_pk_mul_f32 v[64:65], v[64:65], v[80:81]
	v_mov_b32_e32 v66, v71
	v_add_f32_e32 v64, v64, v65
	v_mul_f32_e32 v75, v160, v64
	v_pk_mul_f32 v[64:65], v[66:67], v[86:87]
	v_mov_b32_e32 v70, v67
	v_sub_f32_e32 v64, v64, v65
	v_mul_f32_e32 v66, v160, v64
	v_pk_mul_f32 v[64:65], v[70:71], v[86:87]
	s_nop 0
	v_add_f32_e32 v64, v64, v65
	v_mul_f32_e32 v67, v160, v64
	v_cvt_pk_bf16_f32 v64, v76, v74
	v_cvt_pk_bf16_f32 v65, v69, v66
	v_cvt_pk_bf16_f32 v66, v77, v68
	v_cvt_pk_bf16_f32 v67, v75, v67
	v_mov_b32_e32 v232, v64
	v_mov_b32_e32 v233, v65
	v_mov_b32_e32 v234, v66
	v_mov_b32_e32 v235, v67
	global_store_dwordx4 v[72:73], v[232:235], off offset:256
	v_lshlrev_b32_e32 v64, 7, v150
	v_and_b32_e32 v132, 0x7e780, v64
	v_lshl_add_u64 v[64:65], v[134:135], 0, v[132:133]
	v_lshl_add_u64 v[68:69], v[136:137], 0, v[132:133]
	global_load_dwordx4 v[64:67], v[64:65], off
	s_nop 0
	global_load_dwordx4 v[68:71], v[68:69], off
	v_mov_b32_e32 v72, v60
	v_mov_b32_e32 v73, v56
	v_mov_b32_e32 v74, v56
	v_mov_b32_e32 v75, v60
	v_mov_b32_e32 v60, v57
	v_lshlrev_b64 v[76:77], 13, v[150:151]
	s_waitcnt vmcnt(0)
	v_mov_b32_e32 v78, v64
	v_mov_b32_e32 v79, v68
	v_pk_mul_f32 v[72:73], v[72:73], v[78:79]
	v_mov_b32_e32 v68, v65
	v_sub_f32_e32 v56, v72, v73
	v_pk_mul_f32 v[72:73], v[74:75], v[78:79]
	v_mul_f32_e32 v80, v160, v56
	v_add_f32_e32 v56, v72, v73
	v_mul_f32_e32 v72, v160, v56
	v_mov_b32_e32 v56, v61
	v_pk_mul_f32 v[64:65], v[56:57], v[68:69]
	s_nop 0
	v_sub_f32_e32 v56, v64, v65
	v_mul_f32_e32 v64, v160, v56
	v_pk_mul_f32 v[56:57], v[60:61], v[68:69]
	v_mov_b32_e32 v60, v66
	v_add_f32_e32 v56, v56, v57
	v_mul_f32_e32 v65, v160, v56
	v_mov_b32_e32 v56, v62
	v_mov_b32_e32 v57, v58
	v_mov_b32_e32 v61, v70
	v_pk_mul_f32 v[56:57], v[56:57], v[60:61]
	v_mov_b32_e32 v70, v67
	v_sub_f32_e32 v56, v56, v57
	v_mul_f32_e32 v66, v160, v56
	v_mov_b32_e32 v56, v58
	v_mov_b32_e32 v57, v62
	v_pk_mul_f32 v[56:57], v[56:57], v[60:61]
	v_mov_b32_e32 v58, v63
	v_add_f32_e32 v56, v56, v57
	v_mul_f32_e32 v73, v160, v56
	v_pk_mul_f32 v[56:57], v[58:59], v[70:71]
	v_mov_b32_e32 v62, v59
	v_sub_f32_e32 v56, v56, v57
	v_mul_f32_e32 v67, v160, v56
	v_pk_mul_f32 v[56:57], v[62:63], v[70:71]
	v_cvt_pk_bf16_f32 v58, v80, v64
	v_cvt_pk_bf16_f32 v59, v66, v67
	v_cvt_pk_bf16_f32 v62, v72, v65
	s_nop 0
	v_add_f32_e32 v56, v56, v57
	v_mul_f32_e32 v63, v160, v56
	v_lshl_add_u64 v[56:57], s[96:97], 0, v[76:77]
	v_lshl_add_u64 v[56:57], v[56:57], 0, s[30:31]
	v_lshl_add_u64 v[56:57], v[56:57], 0, s[6:7]
	v_lshl_add_u64 v[56:57], v[56:57], 0, v[230:231]
	v_cvt_pk_bf16_f32 v63, v73, v63
	v_mov_b32_e32 v232, v58
	v_mov_b32_e32 v233, v59
	v_mov_b32_e32 v234, v62
	v_mov_b32_e32 v235, v63
	global_store_dwordx4 v[56:57], v[232:235], off
	v_mov_b32_e32 v58, v52
	v_mov_b32_e32 v59, v48
	v_pk_mul_f32 v[58:59], v[58:59], v[78:79]
	s_nop 0
	v_sub_f32_e32 v58, v58, v59
	v_mul_f32_e32 v62, v160, v58
	v_mov_b32_e32 v58, v48
	v_mov_b32_e32 v59, v52
	v_pk_mul_f32 v[58:59], v[58:59], v[78:79]
	v_mov_b32_e32 v52, v49
	v_add_f32_e32 v48, v58, v59
	v_mul_f32_e32 v63, v160, v48
	v_mov_b32_e32 v48, v53
	v_pk_mul_f32 v[58:59], v[48:49], v[68:69]
	s_nop 0
	v_sub_f32_e32 v48, v58, v59
	v_mul_f32_e32 v58, v160, v48
	v_pk_mul_f32 v[48:49], v[52:53], v[68:69]
	s_nop 0
	v_add_f32_e32 v48, v48, v49
	v_mul_f32_e32 v52, v160, v48
	v_mov_b32_e32 v48, v54
	v_mov_b32_e32 v49, v50
	v_pk_mul_f32 v[48:49], v[48:49], v[60:61]
	s_nop 0
	v_sub_f32_e32 v48, v48, v49
	v_mul_f32_e32 v53, v160, v48
	v_mov_b32_e32 v48, v50
	v_mov_b32_e32 v49, v54
	v_pk_mul_f32 v[48:49], v[48:49], v[60:61]
	v_mov_b32_e32 v50, v55
	v_add_f32_e32 v48, v48, v49
	v_mul_f32_e32 v59, v160, v48
	v_pk_mul_f32 v[48:49], v[50:51], v[70:71]
	v_mov_b32_e32 v54, v51
	v_sub_f32_e32 v48, v48, v49
	v_mul_f32_e32 v50, v160, v48
	v_pk_mul_f32 v[48:49], v[54:55], v[70:71]
	s_nop 0
	v_add_f32_e32 v48, v48, v49
	v_mul_f32_e32 v51, v160, v48
	v_cvt_pk_bf16_f32 v48, v62, v58
	v_cvt_pk_bf16_f32 v49, v53, v50
	v_cvt_pk_bf16_f32 v50, v63, v52
	v_cvt_pk_bf16_f32 v51, v59, v51
	v_mov_b32_e32 v232, v48
	v_mov_b32_e32 v233, v49
	v_mov_b32_e32 v234, v50
	v_mov_b32_e32 v235, v51
	global_store_dwordx4 v[56:57], v[232:235], off offset:256
	v_add_u32_e32 v56, 0x90, v148
	v_lshlrev_b32_e32 v48, 7, v56
	v_and_b32_e32 v132, 0x7ef80, v48
	v_lshl_add_u64 v[48:49], v[134:135], 0, v[132:133]
	v_lshl_add_u64 v[52:53], v[136:137], 0, v[132:133]
	global_load_dwordx4 v[48:51], v[48:49], off
	s_nop 0
	global_load_dwordx4 v[52:55], v[52:53], off
	v_mov_b32_e32 v58, v44
	v_mov_b32_e32 v59, v40
	v_ashrrev_i32_e32 v57, 31, v56
	v_lshlrev_b64 v[56:57], 13, v[56:57]
	s_waitcnt vmcnt(0)
; __device__ __forceinline__ unsigned cvt_pk_bf16(float lo, float hi) { unsigned r; asm volatile("v_cvt_pk_bf16_f32 %0, %1, %2" : "=v"(r) : "v"(lo), "v"(hi)); return r; }
;     __device__ __forceinline__ void operator()(const f32x4 (&acc)[2][2][4][2], const Unit& u, int wr, int wc, int fr, int fq) const {
;     ...
;                 for (int m = 0; m < 4; ++m) { const int row = row0 + ai * 128 + m * 16, t = row & 4095;
;                     const f32x4 c4 = *(const f32x4*)(cs + t * 32 + j0), s4 = *(const f32x4*)(sn + t * 32 + j0);
; #pragma unroll
;                     for (int bj = 0; bj < 2; ++bj) { const int hh = 2 * bj + (wc >> 1);
;                         const f32x4 x1 = acc[ai][bj][m][0], x2 = acc[ai][bj][m][1]; float o1[4], o2[4];
; #pragma unroll
;                         for (int i = 0; i < 4; ++i) { o1[i] = (x1[i] * c4[i] - x2[i] * s4[i]) * qs; o2[i] = (x2[i] * c4[i] + x1[i] * s4[i]) * qs; }
;                         u16* dst = QK + (size_t)row * 4096 + u.pn * 256 + 64 * hh + j0;
;                         u32x2 a, b; a[0] = cvt_pk_bf16(o1[0], o1[1]); a[1] = cvt_pk_bf16(o1[2], o1[3]); b[0] = cvt_pk_bf16(o2[0], o2[1]); b[1] = cvt_pk_bf16(o2[2], o2[3]);
;                         *(u32x2*)dst = a; *(u32x2*)(dst + 32) = b; } }
	v_mov_b32_e32 v60, v48
	v_mov_b32_e32 v61, v52
	v_pk_mul_f32 v[58:59], v[58:59], v[60:61]
	v_mov_b32_e32 v52, v49
	v_sub_f32_e32 v48, v58, v59
	v_mov_b32_e32 v58, v40
	v_mov_b32_e32 v59, v44
	v_pk_mul_f32 v[58:59], v[58:59], v[60:61]
	v_mul_f32_e32 v62, v160, v48
	v_add_f32_e32 v40, v58, v59
	v_mul_f32_e32 v58, v160, v40
	v_mov_b32_e32 v40, v45
	v_pk_mul_f32 v[48:49], v[40:41], v[52:53]
	v_mov_b32_e32 v44, v41
	v_sub_f32_e32 v40, v48, v49
	v_mul_f32_e32 v48, v160, v40
	v_pk_mul_f32 v[40:41], v[44:45], v[52:53]
	v_mov_b32_e32 v44, v50
	v_add_f32_e32 v40, v40, v41
	v_mul_f32_e32 v49, v160, v40
	v_mov_b32_e32 v40, v46
	v_mov_b32_e32 v41, v42
	v_mov_b32_e32 v45, v54
	v_pk_mul_f32 v[40:41], v[40:41], v[44:45]
	v_mov_b32_e32 v54, v51
	v_sub_f32_e32 v40, v40, v41
	v_mul_f32_e32 v50, v160, v40
	v_mov_b32_e32 v40, v42
	v_mov_b32_e32 v41, v46
	v_pk_mul_f32 v[40:41], v[40:41], v[44:45]
	v_mov_b32_e32 v42, v47
	v_add_f32_e32 v40, v40, v41
	v_mul_f32_e32 v59, v160, v40
	v_pk_mul_f32 v[40:41], v[42:43], v[54:55]
	v_mov_b32_e32 v46, v43
	v_sub_f32_e32 v40, v40, v41
	v_mul_f32_e32 v51, v160, v40
	v_pk_mul_f32 v[40:41], v[46:47], v[54:55]
	v_cvt_pk_bf16_f32 v42, v62, v48
	v_cvt_pk_bf16_f32 v43, v50, v51
	v_cvt_pk_bf16_f32 v46, v58, v49
	s_nop 0
	v_add_f32_e32 v40, v40, v41
	v_mul_f32_e32 v47, v160, v40
	v_lshl_add_u64 v[40:41], s[96:97], 0, v[56:57]
	v_lshl_add_u64 v[40:41], v[40:41], 0, s[30:31]
	v_lshl_add_u64 v[40:41], v[40:41], 0, s[6:7]
	v_lshl_add_u64 v[40:41], v[40:41], 0, v[230:231]
	v_cvt_pk_bf16_f32 v47, v59, v47
	v_mov_b32_e32 v232, v42
	v_mov_b32_e32 v233, v43
	v_mov_b32_e32 v234, v46
	v_mov_b32_e32 v235, v47
	global_store_dwordx4 v[40:41], v[232:235], off
	v_mov_b32_e32 v42, v36
	v_mov_b32_e32 v43, v32
	v_pk_mul_f32 v[42:43], v[42:43], v[60:61]
	s_nop 0
	v_sub_f32_e32 v42, v42, v43
	v_mul_f32_e32 v46, v160, v42
	v_mov_b32_e32 v42, v32
	v_mov_b32_e32 v43, v36
	v_pk_mul_f32 v[42:43], v[42:43], v[60:61]
	v_mov_b32_e32 v36, v33
	v_add_f32_e32 v32, v42, v43
	v_mul_f32_e32 v47, v160, v32
	v_mov_b32_e32 v32, v37
	v_pk_mul_f32 v[42:43], v[32:33], v[52:53]
	s_nop 0
	v_sub_f32_e32 v32, v42, v43
	v_mul_f32_e32 v42, v160, v32
	v_pk_mul_f32 v[32:33], v[36:37], v[52:53]
	s_nop 0
	v_add_f32_e32 v32, v32, v33
	v_mul_f32_e32 v36, v160, v32
	v_mov_b32_e32 v32, v38
	v_mov_b32_e32 v33, v34
	v_pk_mul_f32 v[32:33], v[32:33], v[44:45]
	s_nop 0
	v_sub_f32_e32 v32, v32, v33
	v_mul_f32_e32 v37, v160, v32
	v_mov_b32_e32 v32, v34
	v_mov_b32_e32 v33, v38
	v_pk_mul_f32 v[32:33], v[32:33], v[44:45]
	v_mov_b32_e32 v34, v39
	v_add_f32_e32 v32, v32, v33
	v_mul_f32_e32 v43, v160, v32
	v_pk_mul_f32 v[32:33], v[34:35], v[54:55]
	v_mov_b32_e32 v38, v35
	v_sub_f32_e32 v32, v32, v33
	v_mul_f32_e32 v34, v160, v32
	v_pk_mul_f32 v[32:33], v[38:39], v[54:55]
	s_nop 0
	v_add_f32_e32 v32, v32, v33
	v_mul_f32_e32 v35, v160, v32
	v_cvt_pk_bf16_f32 v32, v46, v42
	v_cvt_pk_bf16_f32 v33, v37, v34
	v_cvt_pk_bf16_f32 v34, v47, v36
	v_cvt_pk_bf16_f32 v35, v43, v35
	v_mov_b32_e32 v232, v32
	v_mov_b32_e32 v233, v33
	v_mov_b32_e32 v234, v34
	v_mov_b32_e32 v235, v35
	global_store_dwordx4 v[40:41], v[232:235], off offset:256
	v_add_u32_e32 v40, 0xa0, v148
	v_lshlrev_b32_e32 v32, 7, v40
	v_and_b32_e32 v132, 0x7f780, v32
	v_lshl_add_u64 v[32:33], v[134:135], 0, v[132:133]
	v_lshl_add_u64 v[36:37], v[136:137], 0, v[132:133]
	global_load_dwordx4 v[32:35], v[32:33], off
	s_nop 0
	global_load_dwordx4 v[36:39], v[36:37], off
	v_mov_b32_e32 v42, v28
	v_mov_b32_e32 v43, v24
	v_ashrrev_i32_e32 v41, 31, v40
	v_lshlrev_b64 v[40:41], 13, v[40:41]
	s_waitcnt vmcnt(0)
; __device__ __forceinline__ unsigned cvt_pk_bf16(float lo, float hi) { unsigned r; asm volatile("v_cvt_pk_bf16_f32 %0, %1, %2" : "=v"(r) : "v"(lo), "v"(hi)); return r; }
;     __device__ __forceinline__ void operator()(const f32x4 (&acc)[2][2][4][2], const Unit& u, int wr, int wc, int fr, int fq) const {
;     ...
;                 for (int m = 0; m < 4; ++m) { const int row = row0 + ai * 128 + m * 16, t = row & 4095;
;                     const f32x4 c4 = *(const f32x4*)(cs + t * 32 + j0), s4 = *(const f32x4*)(sn + t * 32 + j0);
; #pragma unroll
;                     for (int bj = 0; bj < 2; ++bj) { const int hh = 2 * bj + (wc >> 1);
;                         const f32x4 x1 = acc[ai][bj][m][0], x2 = acc[ai][bj][m][1]; float o1[4], o2[4];
; #pragma unroll
;                         for (int i = 0; i < 4; ++i) { o1[i] = (x1[i] * c4[i] - x2[i] * s4[i]) * qs; o2[i] = (x2[i] * c4[i] + x1[i] * s4[i]) * qs; }
;                         u16* dst = QK + (size_t)row * 4096 + u.pn * 256 + 64 * hh + j0;
;                         u32x2 a, b; a[0] = cvt_pk_bf16(o1[0], o1[1]); a[1] = cvt_pk_bf16(o1[2], o1[3]); b[0] = cvt_pk_bf16(o2[0], o2[1]); b[1] = cvt_pk_bf16(o2[2], o2[3]);
;                         *(u32x2*)dst = a; *(u32x2*)(dst + 32) = b; } }
	v_mov_b32_e32 v44, v32
	v_mov_b32_e32 v45, v36
	v_pk_mul_f32 v[42:43], v[42:43], v[44:45]
	v_mov_b32_e32 v36, v33
	v_sub_f32_e32 v32, v42, v43
	v_mov_b32_e32 v42, v24
	v_mov_b32_e32 v43, v28
	v_pk_mul_f32 v[42:43], v[42:43], v[44:45]
	v_mul_f32_e32 v46, v160, v32
	v_add_f32_e32 v24, v42, v43
	v_mul_f32_e32 v42, v160, v24
	v_mov_b32_e32 v24, v29
	v_pk_mul_f32 v[32:33], v[24:25], v[36:37]
	v_mov_b32_e32 v28, v25
	v_sub_f32_e32 v24, v32, v33
	v_mul_f32_e32 v32, v160, v24
	v_pk_mul_f32 v[24:25], v[28:29], v[36:37]
	v_mov_b32_e32 v28, v34
	v_add_f32_e32 v24, v24, v25
	v_mul_f32_e32 v33, v160, v24
	v_mov_b32_e32 v24, v30
	v_mov_b32_e32 v25, v26
	v_mov_b32_e32 v29, v38
	v_pk_mul_f32 v[24:25], v[24:25], v[28:29]
	v_mov_b32_e32 v38, v35
	v_sub_f32_e32 v24, v24, v25
	v_mul_f32_e32 v34, v160, v24
	v_mov_b32_e32 v24, v26
	v_mov_b32_e32 v25, v30
	v_pk_mul_f32 v[24:25], v[24:25], v[28:29]
	v_mov_b32_e32 v26, v31
	v_add_f32_e32 v24, v24, v25
	v_mul_f32_e32 v43, v160, v24
	v_pk_mul_f32 v[24:25], v[26:27], v[38:39]
	v_mov_b32_e32 v30, v27
	v_sub_f32_e32 v24, v24, v25
	v_mul_f32_e32 v35, v160, v24
	v_pk_mul_f32 v[24:25], v[30:31], v[38:39]
	v_cvt_pk_bf16_f32 v26, v46, v32
	v_cvt_pk_bf16_f32 v27, v34, v35
	v_cvt_pk_bf16_f32 v30, v42, v33
	s_nop 0
	v_add_f32_e32 v24, v24, v25
	v_mul_f32_e32 v31, v160, v24
	v_lshl_add_u64 v[24:25], s[96:97], 0, v[40:41]
	v_lshl_add_u64 v[24:25], v[24:25], 0, s[30:31]
	v_lshl_add_u64 v[24:25], v[24:25], 0, s[6:7]
	v_lshl_add_u64 v[24:25], v[24:25], 0, v[230:231]
	v_cvt_pk_bf16_f32 v31, v43, v31
	v_mov_b32_e32 v232, v26
	v_mov_b32_e32 v233, v27
	v_mov_b32_e32 v234, v30
	v_mov_b32_e32 v235, v31
	global_store_dwordx4 v[24:25], v[232:235], off
	v_mov_b32_e32 v26, v20
	v_mov_b32_e32 v27, v16
	v_pk_mul_f32 v[26:27], v[26:27], v[44:45]
	s_nop 0
	v_sub_f32_e32 v26, v26, v27
	v_mul_f32_e32 v30, v160, v26
	v_mov_b32_e32 v26, v16
	v_mov_b32_e32 v27, v20
	v_pk_mul_f32 v[26:27], v[26:27], v[44:45]
	v_mov_b32_e32 v20, v17
	v_add_f32_e32 v16, v26, v27
	v_mul_f32_e32 v31, v160, v16
	v_mov_b32_e32 v16, v21
	v_pk_mul_f32 v[26:27], v[16:17], v[36:37]
	s_nop 0
	v_sub_f32_e32 v16, v26, v27
	v_mul_f32_e32 v26, v160, v16
	v_pk_mul_f32 v[16:17], v[20:21], v[36:37]
	s_nop 0
	v_add_f32_e32 v16, v16, v17
	v_mul_f32_e32 v20, v160, v16
	v_mov_b32_e32 v16, v22
	v_mov_b32_e32 v17, v18
	v_pk_mul_f32 v[16:17], v[16:17], v[28:29]
	s_nop 0
	v_sub_f32_e32 v16, v16, v17
	v_mul_f32_e32 v21, v160, v16
	v_mov_b32_e32 v16, v18
	v_mov_b32_e32 v17, v22
	v_pk_mul_f32 v[16:17], v[16:17], v[28:29]
	v_mov_b32_e32 v18, v23
	v_add_f32_e32 v16, v16, v17
	v_mul_f32_e32 v27, v160, v16
	v_pk_mul_f32 v[16:17], v[18:19], v[38:39]
	v_mov_b32_e32 v22, v19
	v_sub_f32_e32 v16, v16, v17
	v_mul_f32_e32 v18, v160, v16
	v_pk_mul_f32 v[16:17], v[22:23], v[38:39]
	s_nop 0
	v_add_f32_e32 v16, v16, v17
	v_mul_f32_e32 v19, v160, v16
	v_cvt_pk_bf16_f32 v16, v30, v26
	v_cvt_pk_bf16_f32 v17, v21, v18
	v_cvt_pk_bf16_f32 v18, v31, v20
	v_cvt_pk_bf16_f32 v19, v27, v19
	v_mov_b32_e32 v232, v16
	v_mov_b32_e32 v233, v17
	v_mov_b32_e32 v234, v18
	v_mov_b32_e32 v235, v19
	global_store_dwordx4 v[24:25], v[232:235], off offset:256
	v_add_u32_e32 v24, 0xb0, v148
	v_lshlrev_b32_e32 v16, 7, v24
	v_and_b32_e32 v132, 0x7ff80, v16
	v_lshl_add_u64 v[16:17], v[134:135], 0, v[132:133]
	v_lshl_add_u64 v[20:21], v[136:137], 0, v[132:133]
	global_load_dwordx4 v[16:19], v[16:17], off
	s_nop 0
	global_load_dwordx4 v[20:23], v[20:21], off
	v_mov_b32_e32 v26, v12
	v_mov_b32_e32 v27, v8
	v_ashrrev_i32_e32 v25, 31, v24
	v_lshlrev_b64 v[24:25], 13, v[24:25]
	s_waitcnt vmcnt(0)
	v_mov_b32_e32 v28, v16
	v_mov_b32_e32 v29, v20
	v_pk_mul_f32 v[26:27], v[26:27], v[28:29]
	v_mov_b32_e32 v20, v17
	v_sub_f32_e32 v16, v26, v27
	v_mov_b32_e32 v26, v8
	v_mov_b32_e32 v27, v12
	v_pk_mul_f32 v[26:27], v[26:27], v[28:29]
	v_mul_f32_e32 v30, v160, v16
	v_add_f32_e32 v8, v26, v27
	v_mul_f32_e32 v26, v160, v8
	v_mov_b32_e32 v8, v13
	v_pk_mul_f32 v[16:17], v[8:9], v[20:21]
	v_mov_b32_e32 v12, v9
	v_sub_f32_e32 v8, v16, v17
	v_mul_f32_e32 v16, v160, v8
	v_pk_mul_f32 v[8:9], v[12:13], v[20:21]
	v_mov_b32_e32 v12, v18
	v_add_f32_e32 v8, v8, v9
	v_mul_f32_e32 v17, v160, v8
	v_mov_b32_e32 v8, v14
	v_mov_b32_e32 v9, v10
	v_mov_b32_e32 v13, v22
	v_pk_mul_f32 v[8:9], v[8:9], v[12:13]
	v_mov_b32_e32 v22, v19
	v_sub_f32_e32 v8, v8, v9
	v_mul_f32_e32 v18, v160, v8
	v_mov_b32_e32 v8, v10
	v_mov_b32_e32 v9, v14
	v_pk_mul_f32 v[8:9], v[8:9], v[12:13]
	v_mov_b32_e32 v10, v15
	v_add_f32_e32 v8, v8, v9
	v_mul_f32_e32 v27, v160, v8
	v_pk_mul_f32 v[8:9], v[10:11], v[22:23]
	v_mov_b32_e32 v14, v11
	v_sub_f32_e32 v8, v8, v9
	v_mul_f32_e32 v19, v160, v8
	v_pk_mul_f32 v[8:9], v[14:15], v[22:23]
	v_cvt_pk_bf16_f32 v10, v30, v16
	v_cvt_pk_bf16_f32 v11, v18, v19
	v_cvt_pk_bf16_f32 v14, v26, v17
	s_nop 0
	v_add_f32_e32 v8, v8, v9
	v_mul_f32_e32 v15, v160, v8
	v_lshl_add_u64 v[8:9], s[96:97], 0, v[24:25]
	v_lshl_add_u64 v[8:9], v[8:9], 0, s[30:31]
	v_lshl_add_u64 v[8:9], v[8:9], 0, s[6:7]
	v_lshl_add_u64 v[8:9], v[8:9], 0, v[230:231]
	v_cvt_pk_bf16_f32 v15, v27, v15
	v_mov_b32_e32 v232, v10
	v_mov_b32_e32 v233, v11
	v_mov_b32_e32 v234, v14
	v_mov_b32_e32 v235, v15
	global_store_dwordx4 v[8:9], v[232:235], off
	v_mov_b32_e32 v10, v4
	v_mov_b32_e32 v11, v0
	v_pk_mul_f32 v[10:11], v[10:11], v[28:29]
	s_nop 0
	v_sub_f32_e32 v10, v10, v11
	v_mul_f32_e32 v14, v160, v10
	v_mov_b32_e32 v10, v0
	v_mov_b32_e32 v11, v4
	v_pk_mul_f32 v[10:11], v[10:11], v[28:29]
	v_mov_b32_e32 v4, v1
	v_add_f32_e32 v0, v10, v11
	v_mul_f32_e32 v15, v160, v0
	v_mov_b32_e32 v0, v5
	v_pk_mul_f32 v[10:11], v[0:1], v[20:21]
	s_nop 0
	v_sub_f32_e32 v0, v10, v11
	v_mul_f32_e32 v10, v160, v0
	v_pk_mul_f32 v[0:1], v[4:5], v[20:21]
	s_nop 0
	v_add_f32_e32 v0, v0, v1
	v_mul_f32_e32 v4, v160, v0
	v_mov_b32_e32 v0, v6
	v_mov_b32_e32 v1, v2
	v_pk_mul_f32 v[0:1], v[0:1], v[12:13]
	s_nop 0
	v_sub_f32_e32 v0, v0, v1
	v_mul_f32_e32 v5, v160, v0
	v_mov_b32_e32 v0, v2
	v_mov_b32_e32 v1, v6
	v_pk_mul_f32 v[0:1], v[0:1], v[12:13]
	v_mov_b32_e32 v2, v7
	v_add_f32_e32 v0, v0, v1
	v_mul_f32_e32 v11, v160, v0
	v_pk_mul_f32 v[0:1], v[2:3], v[22:23]
	v_mov_b32_e32 v6, v3
	v_sub_f32_e32 v0, v0, v1
	v_mul_f32_e32 v2, v160, v0
	v_pk_mul_f32 v[0:1], v[6:7], v[22:23]
	s_nop 0
	v_add_f32_e32 v0, v0, v1
	v_mul_f32_e32 v3, v160, v0
	v_cvt_pk_bf16_f32 v0, v14, v10
	v_cvt_pk_bf16_f32 v1, v5, v2
	v_cvt_pk_bf16_f32 v2, v15, v4
	v_cvt_pk_bf16_f32 v3, v11, v3
	v_mov_b32_e32 v232, v0
	v_mov_b32_e32 v233, v1
	v_mov_b32_e32 v234, v2
	v_mov_b32_e32 v235, v3
	global_store_dwordx4 v[8:9], v[232:235], off offset:256
	s_branch .LBB0_1953
